# P13 block permutation: chunk blocks paired per CU, conversion blocks on the other CUs (on top of P4 remap)
# baseline (speedup 1.0000x reference)
.LBB0_2445:
	s_or_b64 exec, exec, s[0:1]
	v_readlane_b32 s98, v245, 0
	s_nop 3
	v_writelane_b32 v244, s98, 62
	s_sub_u32 s99, s98, 0x80
	s_cmpk_lt_u32 s99, 0x100
	s_cbranch_scc0 .Lp13r_go
	s_xor_b32 s99, s99, 0x80
	s_add_u32 s99, s99, 0x80
	s_nop 0
	v_writelane_b32 v245, s99, 0
	s_nop 1
.Lp13r_go:
	v_readlane_b32 s0, v245, 0
	v_readlane_b32 s1, v245, 1
	s_mov_b32 s2, s0
	s_cmpk_lt_i32 s0, 0x100
	v_readlane_b32 s4, v245, 7
	s_cselect_b64 s[0:1], -1, 0
	s_cmpk_gt_i32 s2, 0xff
	v_readlane_b32 s6, v245, 9
	s_cselect_b64 s[68:69], -1, 0
	s_cmpk_gt_i32 s6, 0x140
	s_mov_b64 s[2:3], -1
	v_readlane_b32 s5, v245, 8
	v_readlane_b32 s7, v245, 10
	s_cbranch_scc1 .LBB0_2612
	v_writelane_b32 v244, s68, 34
	s_andn2_b64 vcc, exec, s[0:1]
	s_nop 0
	v_writelane_b32 v244, s69, 35
	s_cbranch_vccnz .LBB0_2531
	s_waitcnt vmcnt(0)
	v_lshrrev_b32_e32 v158, 2, v1
	v_and_b32_e32 v12, -4, v1
	v_and_b32_e32 v5, 31, v1
	v_add_u32_e32 v159, 0x11900, v12
	v_add_u32_e32 v160, 0x11800, v12
	v_and_b32_e32 v12, 0xe0, v158
	v_or_b32_e32 v13, v12, v5
	v_bfe_u32 v6, v1, 5, 1
	v_mul_u32_u24_e32 v14, 0x110, v13
	v_lshlrev_b32_e32 v13, 7, v13
	v_lshlrev_b32_e32 v16, 4, v6
	v_sub_u32_e32 v13, v14, v13
	v_add_u32_e32 v163, v13, v16
	v_lshrrev_b32_e32 v13, 1, v1
	v_and_b32_e32 v3, 63, v1
	v_lshlrev_b32_e32 v161, 3, v6
	v_and_b32_e32 v13, 32, v13
	v_or_b32_e32 v162, v14, v161
	v_or_b32_e32 v14, v13, v5
	v_lshlrev_b32_e32 v18, 2, v3
	v_mul_u32_u24_e32 v10, 0x88, v158
	s_movk_i32 s3, 0x90
	v_or_b32_e32 v166, 0x11800, v18
	v_or_b32_e32 v167, 0x11900, v18
	v_lshlrev_b32_e32 v18, 7, v14
	v_lshlrev_b32_e32 v10, 1, v10
	s_movk_i32 s2, 0xfef2
	v_mad_u32_u24 v18, v14, s3, v18
	v_mad_i32_i24 v11, v158, s2, v10
	v_mad_u32_u24 v164, v14, s3, v16
	v_add_u32_e32 v168, v18, v16
	v_mad_i32_i24 v18, v14, s2, v18
	v_cmp_gt_u32_e64 s[2:3], 8, v3
	v_and_b32_e32 v8, 3, v1
	v_lshlrev_b32_e32 v4, 5, v8
	v_writelane_b32 v244, s2, 36
	v_lshlrev_b32_e32 v17, 2, v6
	v_cmp_eq_u32_e64 s[0:1], 0, v3
	v_writelane_b32 v244, s3, 37
	v_cmp_gt_u32_e64 s[2:3], 16, v3
	v_cmp_gt_u32_e64 s[4:5], 2, v3
	v_cmp_gt_u32_e64 s[6:7], 4, v3
	v_writelane_b32 v244, s2, 38
	v_or_b32_e32 v9, 8, v4
	v_or_b32_e32 v165, v17, v12
	v_writelane_b32 v244, s3, 39
	v_cmp_gt_u32_e64 s[2:3], 32, v3
	v_mul_u32_u24_e32 v3, 0x900, v8
	v_lshl_add_u32 v171, v8, 6, v10
	v_writelane_b32 v244, s2, 40
	v_lshlrev_b32_e32 v3, 1, v3
	v_lshlrev_b32_e32 v10, 1, v158
	v_writelane_b32 v244, s3, 41
	v_add_u32_e32 v172, v11, v3
	v_add_u32_e32 v173, v3, v10
	v_mul_u32_u24_e32 v3, 0x48, v9
	v_cmp_le_u32_e64 s[2:3], v14, v165
	v_lshlrev_b32_e32 v3, 1, v3
	v_add_u32_e32 v174, v11, v3
	v_writelane_b32 v244, s2, 42
	v_add_u32_e32 v175, v3, v10
	v_add_u32_e32 v9, 0x480, v3
	v_add_u32_e32 v3, 0x900, v3
	v_writelane_b32 v244, s3, 43
	v_cmp_eq_u32_e64 s[2:3], v14, v165
	v_lshlrev_b32_e32 v2, 4, v8
	v_add_u32_e32 v178, v11, v3
	v_add_u32_e32 v179, v3, v10
	v_mul_u32_u24_e32 v3, 0x480, v8
	v_writelane_b32 v245, s2, 44
	v_or_b32_e32 v8, 1, v165
	v_lshl_add_u32 v180, v3, 1, v11
	v_writelane_b32 v245, s3, 45
	v_cmp_le_u32_e64 s[2:3], v14, v8
	v_mov_b32_e32 v3, 0x11800
	v_lshl_or_b32 v182, v8, 2, v3
	v_writelane_b32 v244, s2, 12
	v_add_u32_e32 v176, v11, v9
	v_add_u32_e32 v177, v9, v10
	v_writelane_b32 v244, s3, 13
	v_cmp_eq_u32_e64 s[2:3], v14, v8
	v_or_b32_e32 v8, 2, v165
	v_cmp_le_u32_e64 s[26:27], v14, v8
	v_writelane_b32 v244, s2, 30
	v_lshl_or_b32 v183, v8, 2, v3
	v_cmp_eq_u32_e64 s[28:29], v14, v8
	v_writelane_b32 v244, s3, 31
	v_or_b32_e32 v8, 3, v165
	s_movk_i32 s2, 0x80
	v_cmp_le_u32_e64 s[30:31], v14, v8
	v_lshl_or_b32 v184, v8, 2, v3
	v_cmp_eq_u32_e64 s[34:35], v14, v8
	v_or_b32_e32 v8, 8, v165
	v_cmp_gt_u32_e64 s[2:3], s2, v1
	v_cmp_le_u32_e64 s[36:37], v14, v8
	v_lshl_or_b32 v185, v8, 2, v3
	v_cmp_eq_u32_e64 s[38:39], v14, v8
	v_or_b32_e32 v8, 9, v165
	v_writelane_b32 v244, s2, 44
	v_cmp_le_u32_e64 s[40:41], v14, v8
	v_lshl_or_b32 v186, v8, 2, v3
	v_cmp_eq_u32_e64 s[42:43], v14, v8
	v_or_b32_e32 v8, 10, v165
	v_writelane_b32 v244, s3, 45
	v_cmp_le_u32_e64 s[44:45], v14, v8
	v_lshl_or_b32 v187, v8, 2, v3
	v_cmp_eq_u32_e64 s[46:47], v14, v8
	v_or_b32_e32 v8, 11, v165
	v_readlane_b32 s8, v244, 14
	v_cmp_le_u32_e64 s[48:49], v14, v8
	v_lshl_or_b32 v188, v8, 2, v3
	v_cmp_eq_u32_e64 s[50:51], v14, v8
	v_or_b32_e32 v8, 16, v165
	v_or_b32_e32 v9, 17, v165
	v_or_b32_e32 v10, 18, v165
	v_or_b32_e32 v11, 19, v165
	v_or_b32_e32 v20, 24, v165
	v_or_b32_e32 v21, 25, v165
	v_or_b32_e32 v22, 26, v165
	v_or_b32_e32 v23, 27, v165
	v_readlane_b32 s22, v244, 28
	v_lshrrev_b32_e32 v7, 6, v1
	v_mov_b32_e32 v138, 0
	v_lshl_or_b32 v181, v165, 2, v3
	v_lshl_or_b32 v189, v8, 2, v3
	v_lshl_or_b32 v190, v9, 2, v3
	v_lshl_or_b32 v191, v10, 2, v3
	v_lshl_or_b32 v192, v11, 2, v3
	v_lshl_or_b32 v193, v20, 2, v3
	v_lshl_or_b32 v194, v21, 2, v3
	v_lshl_or_b32 v195, v22, 2, v3
	v_lshl_or_b32 v196, v23, 2, v3
	v_mul_u32_u24_e32 v3, 0x240, v6
	v_lshlrev_b32_e32 v6, 1, v5
	v_readlane_b32 s23, v244, 29
	s_add_u32 s2, s22, 0x1b7e4000
	v_cmp_ne_u32_e64 s[24:25], 1, v7
	v_cmp_le_u32_e64 s[60:61], v14, v10
	v_cmp_eq_u32_e64 s[62:63], v14, v10
	v_cmp_le_u32_e64 s[64:65], v14, v11
	v_cmp_eq_u32_e64 s[66:67], v14, v11
	v_or_b32_e32 v197, v3, v6
	v_sub_u32_e32 v201, 0x810, v10
	v_sub_u32_e32 v202, 0x810, v11
	v_mul_u32_u24_e32 v3, 0x90, v5
	v_lshlrev_b32_e32 v7, 12, v7
	v_lshlrev_b32_e32 v5, 7, v5
	s_addc_u32 s3, s23, 0
	v_lshlrev_b32_e32 v10, 1, v13
	v_mov_b32_e32 v11, v138
	v_cmp_le_u32_e64 s[52:53], v14, v8
	v_cmp_eq_u32_e64 s[54:55], v14, v8
	v_sub_u32_e32 v199, 0x810, v8
	v_or3_b32 v8, v7, v5, v17
	v_readlane_b32 s9, v244, 15
	v_readlane_b32 s10, v244, 16
	v_readlane_b32 s11, v244, 17
	v_readlane_b32 s12, v244, 18
	v_readlane_b32 s13, v244, 19
	v_readlane_b32 s14, v244, 20
	v_readlane_b32 s15, v244, 21
	v_readlane_b32 s16, v244, 22
	v_readlane_b32 s17, v244, 23
	v_readlane_b32 s18, v244, 24
	v_readlane_b32 s19, v244, 25
	v_readlane_b32 s20, v244, 26
	v_readlane_b32 s21, v244, 27
	v_writelane_b32 v244, s2, 46
	v_lshl_add_u64 v[10:11], s[22:23], 0, v[10:11]
	v_mov_b32_e32 v7, v138
	v_cmp_le_u32_e64 s[56:57], v14, v9
	v_cmp_eq_u32_e64 s[58:59], v14, v9
	v_sub_u32_e32 v200, 0x810, v9
	v_mov_b32_e32 v9, v138
	v_writelane_b32 v244, s3, 47
	v_lshl_add_u64 v[6:7], v[10:11], 0, v[6:7]
	s_mov_b64 s[2:3], 0x16b00000
	v_and_b32_e32 v15, 0x380, v1
	v_lshlrev_b32_e32 v19, 2, v14
	s_add_u32 s90, s22, 0x1bb06000
	v_lshl_add_u64 v[140:141], v[6:7], 0, s[2:3]
	v_lshl_add_u64 v[6:7], v[8:9], 2, s[20:21]
	s_mov_b64 s[2:3], 0x4450000
	v_lshlrev_b32_e32 v150, 1, v2
	v_or_b32_e32 v15, 0x11800, v15
	v_or_b32_e32 v169, 0x11800, v19
	v_or_b32_e32 v170, 0x11900, v19
	v_mul_u32_u24_e32 v19, 0x90, v165
	s_addc_u32 s91, s23, 0
	v_lshl_add_u64 v[142:143], v[6:7], 0, s[2:3]
	v_lshlrev_b32_e32 v146, 1, v4
	v_mbcnt_lo_u32_b32 v2, -1, 0
	v_readlane_b32 s2, v245, 0
	v_cmp_gt_u32_e64 s[84:85], 64, v1
	s_mov_b32 s87, 0
	v_cmp_le_u32_e64 s[68:69], v14, v20
	v_cmp_eq_u32_e64 s[70:71], v14, v20
	v_cmp_le_u32_e64 s[72:73], v14, v21
	v_cmp_eq_u32_e64 s[74:75], v14, v21
	v_cmp_le_u32_e64 s[76:77], v14, v22
	v_cmp_eq_u32_e64 s[78:79], v14, v22
	v_cmp_le_u32_e64 s[80:81], v14, v23
	v_cmp_eq_u32_e64 s[82:83], v14, v23
	s_movk_i32 s33, 0x810
	v_sub_u32_e32 v198, 0x810, v12
	v_sub_u32_e32 v203, 0x810, v20
	v_sub_u32_e32 v204, 0x810, v21
	v_sub_u32_e32 v205, 0x810, v22
	v_sub_u32_e32 v206, 0x810, v23
	s_mov_b64 s[22:23], s[4:5]
	s_mov_b64 s[20:21], s[0:1]
	v_add_u32_e32 v207, 64, v1
	v_add_u32_e32 v208, 64, v158
	s_movk_i32 s19, 0x1800
	v_mov_b64_e32 v[144:145], s[90:91]
	v_mov_b32_e32 v148, v146
	v_mov_b32_e32 v149, v138
	v_mov_b32_e32 v152, v150
	v_mov_b32_e32 v153, v138
	v_mov_b32_e32 v209, 0x3ecc95a3
	v_mov_b32_e32 v210, 0x118fc
	v_add_u32_e32 v211, v15, v16
	v_add_u32_e32 v212, v16, v3
	v_mov_b32_e32 v154, 0x3f317218
	v_mov_b32_e32 v213, 0x7f800000
	v_mov_b32_e32 v214, 0x7fc00000
	v_mov_b32_e32 v215, 0xff800000
	v_mbcnt_hi_u32_b32 v216, -1, v2
	v_add_u32_e32 v217, v18, v19
	s_mov_b32 s18, s2
	v_readlane_b32 s3, v245, 1
	s_branch .LBB0_2449

.LBB0_2745:
	v_readlane_b32 s68, v244, 14
	v_readlane_b32 s69, v244, 15
	v_readlane_b32 s80, v244, 26
	v_readlane_b32 s81, v244, 27
	v_readlane_b32 s82, v244, 28
	v_readlane_b32 s83, v244, 29
	v_readlane_b32 s70, v244, 16
	v_readlane_b32 s71, v244, 17
	v_readlane_b32 s72, v244, 18
	v_readlane_b32 s73, v244, 19
	v_readlane_b32 s74, v244, 20
	v_readlane_b32 s75, v244, 21
	v_readlane_b32 s76, v244, 22
	v_readlane_b32 s77, v244, 23
	v_readlane_b32 s78, v244, 24
	v_readlane_b32 s79, v244, 25
	v_readlane_b32 s98, v244, 62
	s_nop 3
	v_writelane_b32 v245, s98, 0
	s_nop 1
